# grid barrier: acquire invalidate moved from after the release to right after each block's arrival (XCD-last: after its L2 write-back); no invalidate on the release path
# speedup vs baseline: 1.0311x; 1.0303x over previous
.LBB0_476:
	s_or_b64 exec, exec, s[30:31]
	s_waitcnt vmcnt(0)
	v_readfirstlane_b32 s25, v3
	v_sub_u32_e32 v4, 0, v2
	s_nop 0
	v_add_u32_e32 v3, s25, v1
	v_cvt_f32_u32_e32 v1, v2
	v_rcp_iflag_f32_e32 v1, v1
	s_nop 0
	v_mul_f32_e32 v1, 0x4f7ffffe, v1
	v_cvt_u32_f32_e32 v1, v1
	v_mul_lo_u32 v4, v4, v1
	v_mul_hi_u32 v4, v1, v4
	v_add_u32_e32 v1, v1, v4
	v_mul_hi_u32 v1, v3, v1
	v_mul_lo_u32 v4, v1, v2
	v_sub_u32_e32 v4, v3, v4
	v_cmp_ge_u32_e32 vcc, v4, v2
	v_add_u32_e32 v5, 1, v1
	s_nop 0
	v_cndmask_b32_e32 v1, v1, v5, vcc
	v_sub_u32_e32 v5, v4, v2
	v_cndmask_b32_e32 v4, v4, v5, vcc
	v_cmp_ge_u32_e32 vcc, v4, v2
	v_add_u32_e32 v4, 1, v1
	s_nop 0
	v_cndmask_b32_e32 v1, v1, v4, vcc
	v_add_u32_e32 v4, 1, v3
	v_mad_u64_u32 v[2:3], s[26:27], v2, v1, v[2:3]
	v_cmp_ne_u32_e32 vcc, v4, v2
	s_and_saveexec_b64 s[26:27], vcc
	s_xor_b64 s[30:31], exec, s[26:27]
	s_cbranch_execz .LBB0_490
	v_readlane_b32 s26, v254, 39
	v_readlane_b32 s27, v254, 40
	buffer_inv sc1
	s_nop 4
	global_load_dword v0, v129, s[26:27] sc1
	s_waitcnt vmcnt(0)
	v_cmp_eq_u32_e32 vcc, v0, v1
	s_and_saveexec_b64 s[36:37], vcc
	s_cbranch_execz .LBB0_489
	s_mov_b32 s25, 1
	s_mov_b64 s[38:39], 0
	s_branch .LBB0_480

.LBB0_489:
	s_or_b64 exec, exec, s[36:37]
	s_waitcnt vmcnt(0) lgkmcnt(0)
	s_waitcnt vmcnt(0)
.LBB0_490:
	s_andn2_saveexec_b64 s[26:27], s[30:31]
	s_cbranch_execz .LBB0_510
	s_mov_b64 s[30:31], exec
	buffer_wbl2 sc1
	s_waitcnt lgkmcnt(0)
	s_waitcnt vmcnt(0)
	buffer_inv sc1
	s_waitcnt vmcnt(0)
	v_mbcnt_lo_u32_b32 v1, s30, 0
	v_mbcnt_hi_u32_b32 v1, s31, v1
	v_cmp_eq_u32_e32 vcc, 0, v1
	s_and_saveexec_b64 s[36:37], vcc
	s_cbranch_execz .LBB0_493
	s_bcnt1_i32_b64 s25, s[30:31]
	v_readlane_b32 s26, v254, 41
	v_mov_b32_e32 v2, s25
	v_readlane_b32 s27, v254, 42
	s_nop 4
	global_atomic_add v2, v129, v2, s[26:27] sc0

.LBB0_507:
	s_or_b64 exec, exec, s[30:31]
	s_mov_b64 s[30:31], exec
	v_mbcnt_lo_u32_b32 v0, s30, 0
	v_mbcnt_hi_u32_b32 v0, s31, v0
	v_cmp_eq_u32_e32 vcc, 0, v0
	s_waitcnt vmcnt(0)
	s_and_saveexec_b64 s[36:37], vcc
	s_cbranch_execz .LBB0_509
	s_bcnt1_i32_b64 s25, s[30:31]
	v_readlane_b32 s26, v254, 39
	v_mov_b32_e32 v0, s25
	v_readlane_b32 s27, v254, 40
	s_nop 4
